# in-proj GEMM K-loop: LDS fragment reads run two MFMA pairs ahead (fa double-buffered, fb in 3 rotating quads), next half-step first fragments fetched right after the barrier
# speedup vs baseline: 1.0490x; 1.0135x over previous
; #define G_TILE(qq, MT, NT) do { if (banded) { const int bl_ = (qq) / per_band, rem_ = (qq) - bl_ * per_band; NT = rem_ >> 3; MT = (bl_ * 8 + bx) * 8 + (rem_ & 7); } \
;     else { MT = (qq) / g.ntiles; NT = (qq) - MT * g.ntiles; } } while (0)
; #define G_LOAD(AG, BG, kt, RA, RB) do { const int k0_ = (kt) * 64; int ac_ = k0_; if (g.remap) ac_ = k0_ < 512 ? k0_ : (k0_ < 1024 ? g.seg2 + k0_ - 512 : 2304 + k0_ - 1024); \
;     _Pragma("unroll") for (int i = 0; i < 4; ++i) { RA[i] = *(const u32x4*)(AG + (size_t)(64 * i) * g.lda + ac_); RB[i] = *(const u32x4*)(BG + (size_t)(64 * i) * g.K + k0_); } } while (0)
; #define G_WRITE(buf, RA, RB) do { _Pragma("unroll") for (int i = 0; i < 4; ++i) { *(u32x4*)(lds + (buf) * 65536 + i * 8192 + soff) = RA[i]; *(u32x4*)(lds + (buf) * 65536 + 32768 + i * 8192 + soff) = RB[i]; } } while (0)
; template <int EPI>
; DI void gemm_phase(char* lds, const Params& p, const GemmDesc g, int layer) {
;     ...
;   G_TILE(q, mt, nt);
;   const bf16_t* Ag = g.A + (size_t)(mt * 256 + srow) * g.lda + sch * 8;
;   const bf16_t* Bg = g.Bt + (size_t)(nt * 256 + srow) * g.K + sch * 8;
;   u32x4 ra0[4], rb0[4];
;   G_LOAD(Ag, Bg, 0, ra0, rb0); G_WRITE(0, ra0, rb0); G_LOAD(Ag, Bg, 1, ra0, rb0); __syncthreads();
;   for (;;) {
;     const int qn = q + nbx; const bool has_next = qn < qtot;
;     int mtn = mt, ntn = nt; if (has_next) G_TILE(qn, mtn, ntn);
;     const bf16_t* Agn = g.A + (size_t)(mtn * 256 + srow) * g.lda + sch * 8;
;     const bf16_t* Bgn = g.Bt + (size_t)(ntn * 256 + srow) * g.K + sch * 8;
;     f32x16 acc[2][4];
; #pragma unroll
;     for (int a = 0; a < 2; ++a)
; #pragma unroll
;       for (int b = 0; b < 4; ++b)
; #pragma unroll
;         for (int i = 0; i < 16; ++i) acc[a][b][i] = 0.f;
.LBB0_521:
	v_lshl_add_u32 v2, s33, 8, v222
	v_lshl_add_u32 v4, s11, 8, v222
	v_ashrrev_i32_e32 v3, 31, v2
	v_ashrrev_i32_e32 v5, 31, v4
	v_lshlrev_b64 v[2:3], 11, v[2:3]
	v_lshlrev_b64 v[4:5], 11, v[4:5]
	v_lshl_add_u64 v[172:173], v[164:165], 0, v[2:3]
	v_lshl_add_u64 v[174:175], v[168:169], 0, v[4:5]
	s_mov_b64 s[0:1], 0x20000
	v_lshl_add_u64 v[180:181], v[172:173], 0, s[0:1]
	v_lshl_add_u64 v[182:183], v[174:175], 0, s[0:1]
	s_mov_b64 s[0:1], 0x40000
	v_lshl_add_u64 v[184:185], v[172:173], 0, s[0:1]
	v_lshl_add_u64 v[186:187], v[174:175], 0, s[0:1]
	s_mov_b64 s[0:1], 0x60000
	v_lshl_add_u64 v[188:189], v[172:173], 0, s[0:1]
	v_lshl_add_u64 v[190:191], v[174:175], 0, s[0:1]
	s_mov_b64 s[0:1], 0x20080
	v_lshl_add_u64 v[192:193], v[172:173], 0, s[0:1]
	v_lshl_add_u64 v[194:195], v[174:175], 0, s[0:1]
	s_mov_b64 s[0:1], 0x40080
	v_lshl_add_u64 v[196:197], v[172:173], 0, s[0:1]
	v_lshl_add_u64 v[198:199], v[174:175], 0, s[0:1]
	s_mov_b64 s[0:1], 0x60080
	v_mov_b32_e32 v2, 0
	v_lshl_add_u64 v[200:201], v[172:173], 0, s[0:1]
	v_lshl_add_u64 v[202:203], v[174:175], 0, s[0:1]
	s_mov_b32 s40, 0
	s_mov_b64 s[68:69], 0
	v_mov_b32_e32 v3, v2
	v_mov_b32_e32 v4, v2
	v_mov_b32_e32 v5, v2
	v_mov_b32_e32 v6, v2
	v_mov_b32_e32 v7, v2
	v_mov_b32_e32 v8, v2
	v_mov_b32_e32 v9, v2
	v_mov_b32_e32 v10, v2
	v_mov_b32_e32 v11, v2
	v_mov_b32_e32 v12, v2
	v_mov_b32_e32 v13, v2
	v_mov_b32_e32 v14, v2
	v_mov_b32_e32 v15, v2
	v_mov_b32_e32 v16, v2
	v_mov_b32_e32 v17, v2
	v_mov_b32_e32 v18, v2
	v_mov_b32_e32 v19, v2
	v_mov_b32_e32 v20, v2
	v_mov_b32_e32 v21, v2
	v_mov_b32_e32 v22, v2
	v_mov_b32_e32 v23, v2
	v_mov_b32_e32 v24, v2
	v_mov_b32_e32 v25, v2
	v_mov_b32_e32 v26, v2
	v_mov_b32_e32 v27, v2
	v_mov_b32_e32 v28, v2
	v_mov_b32_e32 v29, v2
	v_mov_b32_e32 v30, v2
	v_mov_b32_e32 v31, v2
	v_mov_b32_e32 v32, v2
	v_mov_b32_e32 v33, v2
	v_mov_b32_e32 v66, v2
	v_mov_b32_e32 v67, v2
	v_mov_b32_e32 v68, v2
	v_mov_b32_e32 v69, v2
	v_mov_b32_e32 v70, v2
	v_mov_b32_e32 v71, v2
	v_mov_b32_e32 v72, v2
	v_mov_b32_e32 v73, v2
	v_mov_b32_e32 v74, v2
	v_mov_b32_e32 v75, v2
	v_mov_b32_e32 v76, v2
	v_mov_b32_e32 v77, v2
	v_mov_b32_e32 v78, v2
	v_mov_b32_e32 v79, v2
	v_mov_b32_e32 v80, v2
	v_mov_b32_e32 v81, v2
	v_mov_b32_e32 v82, v2
	v_mov_b32_e32 v83, v2
	v_mov_b32_e32 v84, v2
	v_mov_b32_e32 v85, v2
	v_mov_b32_e32 v86, v2
	v_mov_b32_e32 v87, v2
	v_mov_b32_e32 v88, v2
	v_mov_b32_e32 v89, v2
	v_mov_b32_e32 v90, v2
	v_mov_b32_e32 v91, v2
	v_mov_b32_e32 v92, v2
	v_mov_b32_e32 v93, v2
	v_mov_b32_e32 v94, v2
	v_mov_b32_e32 v95, v2
	v_mov_b32_e32 v96, v2
	v_mov_b32_e32 v97, v2
	v_mov_b32_e32 v34, v2
	v_mov_b32_e32 v35, v2
	v_mov_b32_e32 v36, v2
	v_mov_b32_e32 v37, v2
	v_mov_b32_e32 v38, v2
	v_mov_b32_e32 v39, v2
	v_mov_b32_e32 v40, v2
	v_mov_b32_e32 v41, v2
	v_mov_b32_e32 v42, v2
	v_mov_b32_e32 v43, v2
	v_mov_b32_e32 v44, v2
	v_mov_b32_e32 v45, v2
	v_mov_b32_e32 v46, v2
	v_mov_b32_e32 v47, v2
	v_mov_b32_e32 v48, v2
	v_mov_b32_e32 v49, v2
	v_mov_b32_e32 v50, v2
	v_mov_b32_e32 v51, v2
	v_mov_b32_e32 v52, v2
	v_mov_b32_e32 v53, v2
	v_mov_b32_e32 v54, v2
	v_mov_b32_e32 v55, v2
	v_mov_b32_e32 v56, v2
	v_mov_b32_e32 v57, v2
	v_mov_b32_e32 v58, v2
	v_mov_b32_e32 v59, v2
	v_mov_b32_e32 v60, v2
	v_mov_b32_e32 v61, v2
	v_mov_b32_e32 v62, v2
	v_mov_b32_e32 v63, v2
	v_mov_b32_e32 v64, v2
	v_mov_b32_e32 v65, v2
	v_mov_b32_e32 v98, v2
	v_mov_b32_e32 v99, v2
	v_mov_b32_e32 v100, v2
	v_mov_b32_e32 v101, v2
	v_mov_b32_e32 v102, v2
	v_mov_b32_e32 v103, v2
	v_mov_b32_e32 v104, v2
	v_mov_b32_e32 v105, v2
	v_mov_b32_e32 v106, v2
	v_mov_b32_e32 v107, v2
	v_mov_b32_e32 v108, v2
	v_mov_b32_e32 v109, v2
	v_mov_b32_e32 v110, v2
	v_mov_b32_e32 v111, v2
	v_mov_b32_e32 v112, v2
	v_mov_b32_e32 v113, v2
	v_mov_b32_e32 v114, v2
	v_mov_b32_e32 v115, v2
	v_mov_b32_e32 v116, v2
	v_mov_b32_e32 v117, v2
	v_mov_b32_e32 v118, v2
	v_mov_b32_e32 v119, v2
	v_mov_b32_e32 v120, v2
	v_mov_b32_e32 v121, v2
	v_mov_b32_e32 v122, v2
	v_mov_b32_e32 v123, v2
	v_mov_b32_e32 v124, v2
	v_mov_b32_e32 v125, v2
	v_mov_b32_e32 v126, v2
	v_mov_b32_e32 v127, v2
	v_mov_b32_e32 v128, v2
	v_mov_b32_e32 v129, v2
	v_add_u32_e32 v163, v224, v228
	ds_read_b128 v[208:211], v163
	ds_read_b128 v[232:235], v163 offset:4096
	v_add_u32_e32 v0, v225, v228
	ds_read_b128 v[248:251], v0 offset:36864
	ds_read_b128 v[244:247], v0 offset:32768
	s_branch .LBB0_523
; #define G_LOAD(AG, BG, kt, RA, RB) do { const int k0_ = (kt) * 64; int ac_ = k0_; if (g.remap) ac_ = k0_ < 512 ? k0_ : (k0_ < 1024 ? g.seg2 + k0_ - 512 : 2304 + k0_ - 1024); \
;     _Pragma("unroll") for (int i = 0; i < 4; ++i) { RA[i] = *(const u32x4*)(AG + (size_t)(64 * i) * g.lda + ac_); RB[i] = *(const u32x4*)(BG + (size_t)(64 * i) * g.K + k0_); } } while (0)
; #define G_WRITE(buf, RA, RB) do { _Pragma("unroll") for (int i = 0; i < 4; ++i) { *(u32x4*)(lds + (buf) * 65536 + i * 8192 + soff) = RA[i]; *(u32x4*)(lds + (buf) * 65536 + 32768 + i * 8192 + soff) = RB[i]; } } while (0)
; template <int EPI>
; DI void gemm_phase(char* lds, const Params& p, const GemmDesc g, int layer) {
;     ...
;     for (int kt = 0; kt < nk; kt += 2) {
;       const bool last = kt + 2 >= nk;
;       G_WRITE(1, ra0, rb0);
;       if (!last) G_LOAD(Ag, Bg, kt + 2, ra0, rb0); else if (has_next) G_LOAD(Agn, Bgn, 0, ra0, rb0);
;       G_COMPUTE(0);
;       __syncthreads();
;       if (!last || has_next) G_WRITE(0, ra0, rb0);
;       if (!last) G_LOAD(Ag, Bg, kt + 3, ra0, rb0); else if (has_next) G_LOAD(Agn, Bgn, 1, ra0, rb0);
;       G_COMPUTE(1);
;       __syncthreads();
.LBB0_522:
	s_add_i32 s40, s40, 2
	s_add_u32 s68, s68, 0x100
	s_addc_u32 s69, s69, 0
	s_and_b64 vcc, exec, s[70:71]
	v_add_u32_e32 v0, v227, v228
	ds_read_b128 v[204:207], v0 offset:8192
	s_waitcnt lgkmcnt(1)
	v_mfma_f32_32x32x16_bf16 v[114:129], v[244:247], v[208:211], v[114:129]
	v_mfma_f32_32x32x16_bf16 v[82:97], v[244:247], v[232:235], v[82:97]
	ds_read_b128 v[244:247], v0 offset:12288
	v_add_u32_e32 v163, v226, v229
	ds_read_b128 v[236:239], v163
	ds_read_b128 v[240:243], v163 offset:4096
	v_mfma_f32_32x32x16_bf16 v[98:113], v[248:251], v[208:211], v[98:113]
	v_mfma_f32_32x32x16_bf16 v[66:81], v[248:251], v[232:235], v[66:81]
	v_add_u32_e32 v0, v227, v229
	ds_read_b128 v[248:251], v0 offset:0
	s_waitcnt lgkmcnt(4)
	v_mfma_f32_32x32x16_bf16 v[50:65], v[204:207], v[208:211], v[50:65]
	v_mfma_f32_32x32x16_bf16 v[18:33], v[204:207], v[232:235], v[18:33]
	ds_read_b128 v[204:207], v0 offset:4096
	s_waitcnt lgkmcnt(4)
	v_mfma_f32_32x32x16_bf16 v[34:49], v[244:247], v[208:211], v[34:49]
	v_mfma_f32_32x32x16_bf16 v[2:17], v[244:247], v[232:235], v[2:17]
	ds_read_b128 v[244:247], v0 offset:8192
	s_waitcnt lgkmcnt(2)
	v_mfma_f32_32x32x16_bf16 v[114:129], v[248:251], v[236:239], v[114:129]
	v_mfma_f32_32x32x16_bf16 v[82:97], v[248:251], v[240:243], v[82:97]
	ds_read_b128 v[248:251], v0 offset:12288
	v_add_u32_e32 v163, v226, v230
	ds_read_b128 v[208:211], v163
	ds_read_b128 v[232:235], v163 offset:4096
	s_waitcnt lgkmcnt(4)
	v_mfma_f32_32x32x16_bf16 v[98:113], v[204:207], v[236:239], v[98:113]
	v_mfma_f32_32x32x16_bf16 v[66:81], v[204:207], v[240:243], v[66:81]
	v_add_u32_e32 v0, v227, v230
	ds_read_b128 v[204:207], v0 offset:0
	s_waitcnt lgkmcnt(4)
	v_mfma_f32_32x32x16_bf16 v[50:65], v[244:247], v[236:239], v[50:65]
	v_mfma_f32_32x32x16_bf16 v[18:33], v[244:247], v[240:243], v[18:33]
	ds_read_b128 v[244:247], v0 offset:4096
	s_waitcnt lgkmcnt(4)
	v_mfma_f32_32x32x16_bf16 v[34:49], v[248:251], v[236:239], v[34:49]
	v_mfma_f32_32x32x16_bf16 v[2:17], v[248:251], v[240:243], v[2:17]
	ds_read_b128 v[248:251], v0 offset:8192
	s_waitcnt lgkmcnt(2)
	v_mfma_f32_32x32x16_bf16 v[114:129], v[204:207], v[208:211], v[114:129]
	v_mfma_f32_32x32x16_bf16 v[82:97], v[204:207], v[232:235], v[82:97]
	ds_read_b128 v[204:207], v0 offset:12288
	v_add_u32_e32 v163, v226, v231
	ds_read_b128 v[236:239], v163
	ds_read_b128 v[240:243], v163 offset:4096
	s_waitcnt lgkmcnt(4)
	v_mfma_f32_32x32x16_bf16 v[98:113], v[244:247], v[208:211], v[98:113]
	v_mfma_f32_32x32x16_bf16 v[66:81], v[244:247], v[232:235], v[66:81]
	v_add_u32_e32 v0, v227, v231
	ds_read_b128 v[244:247], v0 offset:0
	s_waitcnt lgkmcnt(4)
	v_mfma_f32_32x32x16_bf16 v[50:65], v[248:251], v[208:211], v[50:65]
	v_mfma_f32_32x32x16_bf16 v[18:33], v[248:251], v[232:235], v[18:33]
	ds_read_b128 v[248:251], v0 offset:4096
	s_waitcnt lgkmcnt(4)
	v_mfma_f32_32x32x16_bf16 v[34:49], v[204:207], v[208:211], v[34:49]
	v_mfma_f32_32x32x16_bf16 v[2:17], v[204:207], v[232:235], v[2:17]
	ds_read_b128 v[204:207], v0 offset:8192
	s_waitcnt lgkmcnt(2)
	v_mfma_f32_32x32x16_bf16 v[114:129], v[244:247], v[236:239], v[114:129]
	v_mfma_f32_32x32x16_bf16 v[82:97], v[244:247], v[240:243], v[82:97]
	ds_read_b128 v[244:247], v0 offset:12288
	s_waitcnt lgkmcnt(2)
	v_mfma_f32_32x32x16_bf16 v[98:113], v[248:251], v[236:239], v[98:113]
	v_mfma_f32_32x32x16_bf16 v[66:81], v[248:251], v[240:243], v[66:81]
	s_waitcnt lgkmcnt(1)
	v_mfma_f32_32x32x16_bf16 v[50:65], v[204:207], v[236:239], v[50:65]
	v_mfma_f32_32x32x16_bf16 v[18:33], v[204:207], v[240:243], v[18:33]
	s_waitcnt lgkmcnt(0)
	s_barrier
	v_add_u32_e32 v163, v224, v228
	ds_read_b128 v[208:211], v163
	ds_read_b128 v[232:235], v163 offset:4096
	v_add_u32_e32 v0, v225, v228
	ds_read_b128 v[248:251], v0 offset:36864
	v_mfma_f32_32x32x16_bf16 v[34:49], v[244:247], v[236:239], v[34:49]
	v_mfma_f32_32x32x16_bf16 v[2:17], v[244:247], v[240:243], v[2:17]
	ds_read_b128 v[244:247], v0 offset:32768
	s_cbranch_vccnz .LBB0_537

; #define G_WRITE(buf, RA, RB) do { _Pragma("unroll") for (int i = 0; i < 4; ++i) { *(u32x4*)(lds + (buf) * 65536 + i * 8192 + soff) = RA[i]; *(u32x4*)(lds + (buf) * 65536 + 32768 + i * 8192 + soff) = RB[i]; } } while (0)
; template <int EPI>
; DI void gemm_phase(char* lds, const Params& p, const GemmDesc g, int layer) {
;     ...
;       G_COMPUTE(0);
;       __syncthreads();
;       if (!last || has_next) G_WRITE(0, ra0, rb0);
.LBB0_529:
	s_or_b64 s[42:43], s[16:17], s[72:73]
	s_andn2_b64 vcc, exec, s[42:43]
	v_add_u32_e32 v0, v225, v228
	ds_read_b128 v[204:207], v0 offset:40960
	s_waitcnt lgkmcnt(1)
	v_mfma_f32_32x32x16_bf16 v[114:129], v[244:247], v[208:211], v[114:129]
	v_mfma_f32_32x32x16_bf16 v[82:97], v[244:247], v[232:235], v[82:97]
	ds_read_b128 v[244:247], v0 offset:45056
	v_add_u32_e32 v163, v224, v229
	ds_read_b128 v[236:239], v163
	ds_read_b128 v[240:243], v163 offset:4096
	v_mfma_f32_32x32x16_bf16 v[98:113], v[248:251], v[208:211], v[98:113]
	v_mfma_f32_32x32x16_bf16 v[66:81], v[248:251], v[232:235], v[66:81]
	v_add_u32_e32 v0, v225, v229
	ds_read_b128 v[248:251], v0 offset:32768
	s_waitcnt lgkmcnt(4)
	v_mfma_f32_32x32x16_bf16 v[50:65], v[204:207], v[208:211], v[50:65]
	v_mfma_f32_32x32x16_bf16 v[18:33], v[204:207], v[232:235], v[18:33]
	ds_read_b128 v[204:207], v0 offset:36864
	s_waitcnt lgkmcnt(4)
	v_mfma_f32_32x32x16_bf16 v[34:49], v[244:247], v[208:211], v[34:49]
	v_mfma_f32_32x32x16_bf16 v[2:17], v[244:247], v[232:235], v[2:17]
	ds_read_b128 v[244:247], v0 offset:40960
	s_waitcnt lgkmcnt(2)
	v_mfma_f32_32x32x16_bf16 v[114:129], v[248:251], v[236:239], v[114:129]
	v_mfma_f32_32x32x16_bf16 v[82:97], v[248:251], v[240:243], v[82:97]
	ds_read_b128 v[248:251], v0 offset:45056
	v_add_u32_e32 v163, v224, v230
	ds_read_b128 v[208:211], v163
	ds_read_b128 v[232:235], v163 offset:4096
	s_waitcnt lgkmcnt(4)
	v_mfma_f32_32x32x16_bf16 v[98:113], v[204:207], v[236:239], v[98:113]
	v_mfma_f32_32x32x16_bf16 v[66:81], v[204:207], v[240:243], v[66:81]
	v_add_u32_e32 v0, v225, v230
	ds_read_b128 v[204:207], v0 offset:32768
	s_waitcnt lgkmcnt(4)
	v_mfma_f32_32x32x16_bf16 v[50:65], v[244:247], v[236:239], v[50:65]
	v_mfma_f32_32x32x16_bf16 v[18:33], v[244:247], v[240:243], v[18:33]
	ds_read_b128 v[244:247], v0 offset:36864
	s_waitcnt lgkmcnt(4)
	v_mfma_f32_32x32x16_bf16 v[34:49], v[248:251], v[236:239], v[34:49]
	v_mfma_f32_32x32x16_bf16 v[2:17], v[248:251], v[240:243], v[2:17]
	ds_read_b128 v[248:251], v0 offset:40960
	s_waitcnt lgkmcnt(2)
	v_mfma_f32_32x32x16_bf16 v[114:129], v[204:207], v[208:211], v[114:129]
	v_mfma_f32_32x32x16_bf16 v[82:97], v[204:207], v[232:235], v[82:97]
	ds_read_b128 v[204:207], v0 offset:45056
	v_add_u32_e32 v163, v224, v231
	ds_read_b128 v[236:239], v163
	ds_read_b128 v[240:243], v163 offset:4096
	s_waitcnt lgkmcnt(4)
	v_mfma_f32_32x32x16_bf16 v[98:113], v[244:247], v[208:211], v[98:113]
	v_mfma_f32_32x32x16_bf16 v[66:81], v[244:247], v[232:235], v[66:81]
	v_add_u32_e32 v0, v225, v231
	ds_read_b128 v[244:247], v0 offset:32768
	s_waitcnt lgkmcnt(4)
	v_mfma_f32_32x32x16_bf16 v[50:65], v[248:251], v[208:211], v[50:65]
	v_mfma_f32_32x32x16_bf16 v[18:33], v[248:251], v[232:235], v[18:33]
	ds_read_b128 v[248:251], v0 offset:36864
	s_waitcnt lgkmcnt(4)
	v_mfma_f32_32x32x16_bf16 v[34:49], v[204:207], v[208:211], v[34:49]
	v_mfma_f32_32x32x16_bf16 v[2:17], v[204:207], v[232:235], v[2:17]
	ds_read_b128 v[204:207], v0 offset:40960
	s_waitcnt lgkmcnt(2)
	v_mfma_f32_32x32x16_bf16 v[114:129], v[244:247], v[236:239], v[114:129]
	v_mfma_f32_32x32x16_bf16 v[82:97], v[244:247], v[240:243], v[82:97]
	ds_read_b128 v[244:247], v0 offset:45056
	s_waitcnt lgkmcnt(2)
	v_mfma_f32_32x32x16_bf16 v[98:113], v[248:251], v[236:239], v[98:113]
	v_mfma_f32_32x32x16_bf16 v[66:81], v[248:251], v[240:243], v[66:81]
	s_waitcnt lgkmcnt(1)
	v_mfma_f32_32x32x16_bf16 v[50:65], v[204:207], v[236:239], v[50:65]
	v_mfma_f32_32x32x16_bf16 v[18:33], v[204:207], v[240:243], v[18:33]
	s_waitcnt lgkmcnt(0)
	s_barrier
	v_add_u32_e32 v163, v226, v228
	ds_read_b128 v[208:211], v163
	ds_read_b128 v[232:235], v163 offset:4096
	v_add_u32_e32 v0, v227, v228
	ds_read_b128 v[248:251], v0 offset:4096
	v_mfma_f32_32x32x16_bf16 v[34:49], v[244:247], v[236:239], v[34:49]
	v_mfma_f32_32x32x16_bf16 v[2:17], v[244:247], v[240:243], v[2:17]
	ds_read_b128 v[244:247], v0 offset:0
	s_cbranch_vccnz .LBB0_532
	s_waitcnt vmcnt(7)
	ds_write_b128 v223, v[130:133]
	s_waitcnt vmcnt(6)
	ds_write_b128 v223, v[134:137] offset:32768
	s_waitcnt vmcnt(5)
	ds_write_b128 v223, v[138:141] offset:8192
	s_waitcnt vmcnt(4)
	ds_write_b128 v223, v[142:145] offset:40960
	s_waitcnt vmcnt(3)
	ds_write_b128 v223, v[146:149] offset:16384
	s_waitcnt vmcnt(2)
	ds_write_b128 v223, v[150:153] offset:49152
	s_waitcnt vmcnt(1)
	ds_write_b128 v223, v[154:157] offset:24576
	s_waitcnt vmcnt(0)
	ds_write_b128 v223, v[158:161] offset:57344
	s_mov_b64 s[72:73], -1
	s_and_b64 vcc, exec, s[70:71]
	s_cbranch_vccnz .LBB0_533

; #define G_LOAD(AG, BG, kt, RA, RB) do { const int k0_ = (kt) * 64; int ac_ = k0_; if (g.remap) ac_ = k0_ < 512 ? k0_ : (k0_ < 1024 ? g.seg2 + k0_ - 512 : 2304 + k0_ - 1024); \
;     _Pragma("unroll") for (int i = 0; i < 4; ++i) { RA[i] = *(const u32x4*)(AG + (size_t)(64 * i) * g.lda + ac_); RB[i] = *(const u32x4*)(BG + (size_t)(64 * i) * g.K + k0_); } } while (0)
; #define G_WRITE(buf, RA, RB) do { _Pragma("unroll") for (int i = 0; i < 4; ++i) { *(u32x4*)(lds + (buf) * 65536 + i * 8192 + soff) = RA[i]; *(u32x4*)(lds + (buf) * 65536 + 32768 + i * 8192 + soff) = RB[i]; } } while (0)
; DI int in_mode(const Params& p, int layer, int n_h, const float*& gain) {
;   int mode = 0; gain = p.mem_qk_g;
;   if ((layer & 1) == 0) { const int e = layer >> 1;
;     if (n_h >= 1536 && n_h < 2048) { mode = 2; gain = p.swa_qk_g + (e * 2) * 64; }
;     else if (n_h >= 2048 && n_h < 2176) { mode = 2; gain = p.swa_qk_g + (e * 2 + 1) * 64; }
;     else if (n_h >= 2304 && n_h < 2560) { mode = 1; gain = p.mem_qk_g + (layer * 2) * 64; }
;   } else { const int o = layer >> 1;
;     if (n_h < 512) { mode = 3; gain = p.ax_qk_g + (o * 2) * 64; }
;     else if (n_h < 640) { mode = 3; gain = p.ax_qk_g + (o * 2 + 1) * 64; }
;     else if (n_h >= 768 && n_h < 1280) { mode = 2; gain = p.diff_qk_g + (o * 2) * 64; }
;     else if (n_h >= 1280 && n_h < 1792) { mode = 2; gain = p.diff_qk_g + (o * 2 + 1) * 64; }
;     else if (n_h >= 2304 && n_h < 2560) { mode = 1; gain = p.mem_qk_g + (layer * 2) * 64; }
;   }
; template <int EPI>
; DI void gemm_phase(char* lds, const Params& p, const GemmDesc g, int layer) {
;     ...
;       if (!last) G_LOAD(Ag, Bg, kt + 2, ra0, rb0); else if (has_next) G_LOAD(Agn, Bgn, 0, ra0, rb0);
;       G_COMPUTE(0);
;       __syncthreads();
;       if (!last || has_next) G_WRITE(0, ra0, rb0);
;       if (!last) G_LOAD(Ag, Bg, kt + 3, ra0, rb0); else if (has_next) G_LOAD(Agn, Bgn, 1, ra0, rb0);
.LBB0_536:
	v_lshl_add_u64 v[206:207], v[176:177], 0, s[68:69]
	v_lshl_add_u64 v[204:205], v[178:179], 0, s[68:69]
	s_waitcnt vmcnt(5)
	v_add_co_u32_e32 v138, vcc, 0x20000, v206
	global_load_dwordx4 v[130:133], v[206:207], off offset:384
	global_load_dwordx4 v[134:137], v[204:205], off offset:384
	v_addc_co_u32_e32 v139, vcc, 0, v207, vcc
	s_waitcnt vmcnt(6)
	v_add_co_u32_e32 v142, vcc, 0x20000, v204
	global_load_dwordx4 v[138:141], v[138:139], off offset:384
	s_nop 0
	v_addc_co_u32_e32 v143, vcc, 0, v205, vcc
	s_waitcnt vmcnt(6)
	v_add_co_u32_e32 v146, vcc, 0x40000, v206
	global_load_dwordx4 v[142:145], v[142:143], off offset:384
	s_nop 0
	v_addc_co_u32_e32 v147, vcc, 0, v207, vcc
	s_waitcnt vmcnt(6)
	v_add_co_u32_e32 v150, vcc, 0x40000, v204
	global_load_dwordx4 v[146:149], v[146:147], off offset:384
	s_nop 0
	v_addc_co_u32_e32 v151, vcc, 0, v205, vcc
	s_waitcnt vmcnt(6)
	v_add_co_u32_e32 v154, vcc, 0x60000, v206
	global_load_dwordx4 v[150:153], v[150:151], off offset:384
	s_nop 0
	v_addc_co_u32_e32 v155, vcc, 0, v207, vcc
	s_waitcnt vmcnt(6)
	v_add_co_u32_e32 v158, vcc, 0x60000, v204
	global_load_dwordx4 v[154:157], v[154:155], off offset:384
	s_nop 0
	v_addc_co_u32_e32 v159, vcc, 0, v205, vcc
	global_load_dwordx4 v[158:161], v[158:159], off offset:384
	s_branch .LBB0_522
.LBB0_537:
	s_waitcnt lgkmcnt(0)
	s_lshl_b32 s40, s38, 8
	s_or_b32 s96, s40, s9
	s_and_b32 s0, s38, 0x7fffff
	s_cmp_lg_u32 s0, 9
	s_cselect_b64 s[74:75], -1, 0
	s_and_b32 s0, s38, 0xfffffe
	s_cmp_eq_u32 s0, 6
	s_cselect_b64 s[68:69], -1, 0
	s_cmp_lg_u32 s0, 6
	s_cselect_b64 s[0:1], -1, 0
	s_cmpk_eq_i32 s96, 0x800
	s_cselect_b64 s[70:71], -1, 0
	s_cmp_lg_u32 s38, 9
	s_mov_b64 s[88:89], -1
	s_cselect_b64 s[72:73], -1, 0
	s_and_b64 vcc, exec, s[24:25]
	s_cbranch_vccz .LBB0_544
	s_mov_b64 s[88:89], 0
	s_mov_b32 s38, 3
	s_cmpk_lt_i32 s96, 0x200
	s_mov_b64 s[92:93], 0
	s_mov_b64 s[16:17], s[2:3]
	s_cbranch_scc1 .LBB0_544
	s_cmpk_lt_u32 s96, 0x280
	s_cbranch_scc1 .LBB0_543
	s_add_i32 s16, s40, 0xfffffd00
	s_cmpk_lt_u32 s16, 0x200
	s_cbranch_scc1 .LBB0_591
	s_addk_i32 s40, 0xfb00
	s_cmpk_lt_u32 s40, 0x200
	s_cselect_b64 s[16:17], -1, 0
	s_cmpk_gt_u32 s40, 0x1ff
	s_cselect_b64 s[92:93], -1, 0
	s_or_b64 s[58:59], s[16:17], s[74:75]
	s_and_b64 s[16:17], s[16:17], exec
	v_readlane_b32 s40, v254, 17
	v_readlane_b32 s43, v254, 20
	v_readlane_b32 s16, v255, 38
	v_readlane_b32 s42, v254, 19
	s_cselect_b32 s17, s16, s43
	v_readlane_b32 s16, v255, 37
	s_cselect_b32 s16, s16, s42
	s_cselect_b32 s38, 2, 0
	s_and_b64 vcc, exec, s[58:59]
	v_readlane_b32 s41, v254, 18
	v_readlane_b32 s44, v254, 21
	v_readlane_b32 s45, v254, 22
	v_readlane_b32 s46, v254, 23
	v_readlane_b32 s47, v254, 24
	v_readlane_b32 s48, v254, 25
	v_readlane_b32 s49, v254, 26
	v_readlane_b32 s50, v254, 27
	v_readlane_b32 s51, v254, 28
	v_readlane_b32 s52, v254, 29
	v_readlane_b32 s53, v254, 30
	v_readlane_b32 s54, v254, 31
	v_readlane_b32 s55, v254, 32
	s_cbranch_vccnz .LBB0_544
	s_mov_b64 s[92:93], 0
	s_mov_b32 s38, 1
	s_mov_b64 s[16:17], s[4:5]
	s_andn2_b64 vcc, exec, s[88:89]
	s_cbranch_vccz .LBB0_545
	s_branch .LBB0_550
